# attention: running max only updated when a chunk raises it by more than 8 log2 units (skips most O rescales; exact softmax)
# baseline (speedup 1.0000x reference)
; DI void attn_item(const Params& p, int l, int item, char* lds) {
;     ...
;     for (int kt = 0; kt < 2; ++kt) {
; #pragma unroll
;       for (int e = 0; e < 16; ++e) s[kt][e] = 0.f;
; #pragma unroll
;       for (int ks = 0; ks < 4; ++ks) {
;         const bf16x8 kf = *(const bf16x8*)(Ks + (m * 64 + kt * 32 + q) * ALD + ks * 16 + hh * 8);
;         s[kt] = __builtin_amdgcn_mfma_f32_32x32x16_bf16(kf, qf[ks], s[kt], 0, 0, 0);
;       }
;     }
;     float mx = -1e30f;
;     const float dbase = qposf - (float)(j * 64 + 4 * hh);
; #pragma unroll
;     for (int kt = 0; kt < 2; ++kt)
; #pragma unroll
;       for (int e = 0; e < 16; ++e) {
;         const float dd = dbase - (float)(kt * 32 + (e & 3) + 8 * (e >> 2));
;         const float v = s[kt][e] * c1 - sl2 * fabsf(dd);
;         s[kt][e] = v; mx = fmaxf(mx, v);
;       }
;     mx = fmaxf(mx, __shfl_xor(mx, 32));
;     const float mnew = fmaxf(mrun, mx);
;     const float alpha = __builtin_amdgcn_exp2f(mrun - mnew);
;     const bool resc = mnew > mrun;
;     mrun = mnew;
;     float ps = 0.f;
; #pragma unroll
;     for (int kt = 0; kt < 2; ++kt)
; #pragma unroll
;       for (int e = 0; e < 16; ++e) { const float pe = __builtin_amdgcn_exp2f(s[kt][e] - mnew); s[kt][e] = pe; ps += pe; }
;     lrun = lrun * alpha + ps;
;     if (__any(resc)) {
.LBB0_600:
	ds_read_b128 v[2:5], v202
	ds_read_b128 v[6:9], v202 offset:32
	ds_read_b128 v[10:13], v202 offset:64
	ds_read_b128 v[214:217], v202 offset:96
	ds_read_b128 v[222:225], v202 offset:4608
	ds_read_b128 v[226:229], v202 offset:4640
	v_cvt_f32_u32_e32 v0, v199
	s_mov_b32 s2, 0xf149f2ca
	v_sub_f32_e32 v0, v187, v0
	s_waitcnt lgkmcnt(5)
	v_mfma_f32_32x32x16_bf16 v[96:111], v[2:5], v[120:123], 0
	ds_read_b128 v[2:5], v202 offset:4672
	s_waitcnt lgkmcnt(5)
	v_mfma_f32_32x32x16_bf16 v[96:111], v[6:9], v[112:115], v[96:111]
	ds_read_b128 v[6:9], v202 offset:4704
	s_waitcnt lgkmcnt(5)
	v_mfma_f32_32x32x16_bf16 v[96:111], v[10:13], v[116:119], v[96:111]
	s_waitcnt lgkmcnt(4)
	v_mfma_f32_32x32x16_bf16 v[96:111], v[214:217], v[124:127], v[96:111]
	s_waitcnt lgkmcnt(3)
	v_mfma_f32_32x32x16_bf16 v[80:95], v[222:225], v[120:123], 0
	s_waitcnt lgkmcnt(2)
	v_mfma_f32_32x32x16_bf16 v[80:95], v[226:229], v[112:115], v[80:95]
	s_waitcnt lgkmcnt(1)
	v_mfma_f32_32x32x16_bf16 v[80:95], v[2:5], v[116:119], v[80:95]
	s_waitcnt lgkmcnt(0)
	v_mfma_f32_32x32x16_bf16 v[80:95], v[6:9], v[124:127], v[80:95]
	v_add_f32_e32 v11, 0xc2640000, v0
	v_add_f32_e32 v9, 0xc24c0000, v0
	v_add_f32_e32 v5, -2.0, v0
	v_mul_f32_e64 v2, v189, |v0|
	v_mul_f32_e64 v5, v189, |v5|
	v_fma_f32 v3, v96, s35, -v2
	v_fma_f32 v96, v98, s35, -v5
	v_add_f32_e32 v5, 0xc0400000, v0
	v_mul_f32_e64 v5, v189, |v5|
	v_fma_f32 v173, v99, s35, -v5
	v_add_f32_e32 v5, 0xc1000000, v0
	v_mul_f32_e64 v5, v189, |v5|
	v_fma_f32 v205, v100, s35, -v5
	v_add_f32_e32 v5, 0xc1100000, v0
	v_mul_f32_e64 v5, v189, |v5|
	v_fma_f32 v206, v101, s35, -v5
	v_add_f32_e32 v5, 0xc1200000, v0
	v_mul_f32_e64 v5, v189, |v5|
	v_fma_f32 v10, v102, s35, -v5
	v_add_f32_e32 v5, 0xc1300000, v0
	v_mul_f32_e64 v5, v189, |v5|
	v_fma_f32 v13, v103, s35, -v5
	v_add_f32_e32 v5, 0xc1800000, v0
	v_mul_f32_e64 v5, v189, |v5|
	v_fma_f32 v15, v104, s35, -v5
	v_add_f32_e32 v5, 0xc1880000, v0
	v_mul_f32_e64 v5, v189, |v5|
	v_fma_f32 v103, v105, s35, -v5
	v_add_f32_e32 v5, 0xc1900000, v0
	v_mul_f32_e64 v5, v189, |v5|
	v_fma_f32 v105, v106, s35, -v5
	v_add_f32_e32 v5, 0xc1980000, v0
	v_mul_f32_e64 v5, v189, |v5|
	v_fma_f32 v107, v107, s35, -v5
	v_add_f32_e32 v5, 0xc1c00000, v0
	v_mul_f32_e64 v5, v189, |v5|
	v_fma_f32 v102, v108, s35, -v5
	v_add_f32_e32 v5, 0xc1c80000, v0
	v_mul_f32_e64 v5, v189, |v5|
	v_fma_f32 v104, v109, s35, -v5
	v_add_f32_e32 v5, 0xc1d00000, v0
	v_mul_f32_e64 v5, v189, |v5|
	v_fma_f32 v106, v110, s35, -v5
	v_add_f32_e32 v5, 0xc1d80000, v0
	v_mul_f32_e64 v5, v189, |v5|
	v_fma_f32 v101, v111, s35, -v5
	v_add_f32_e32 v5, 0xc2000000, v0
	v_mul_f32_e64 v5, v189, |v5|
	v_add_f32_e32 v2, -1.0, v0
	v_fma_f32 v100, v80, s35, -v5
	v_add_f32_e32 v5, 0xc2040000, v0
	v_mul_f32_e64 v2, v189, |v2|
	v_mul_f32_e64 v5, v189, |v5|
	v_fma_f32 v4, v97, s35, -v2
	v_fma_f32 v97, v81, s35, -v5
	v_add_f32_e32 v5, 0xc2080000, v0
	v_mul_f32_e64 v5, v189, |v5|
	v_fma_f32 v98, v82, s35, -v5
	v_add_f32_e32 v5, 0xc20c0000, v0
	v_mul_f32_e64 v5, v189, |v5|
	v_fma_f32 v99, v83, s35, -v5
	v_add_f32_e32 v5, 0xc2200000, v0
	v_mul_f32_e64 v5, v189, |v5|
	v_fma_f32 v80, v84, s35, -v5
	v_add_f32_e32 v5, 0xc2240000, v0
	v_mul_f32_e64 v5, v189, |v5|
	v_max3_f32 v2, v3, s2, v4
	v_fma_f32 v81, v85, s35, -v5
	v_add_f32_e32 v5, 0xc2280000, v0
	v_max3_f32 v2, v2, v96, v173
	v_mul_f32_e64 v5, v189, |v5|
	v_max3_f32 v2, v2, v205, v206
	v_fma_f32 v82, v86, s35, -v5
	v_add_f32_e32 v5, 0xc22c0000, v0
	v_max3_f32 v2, v2, v10, v13
	v_and_b32_e32 v161, 0x7fffffff, v5
	v_mov_b32_e32 v188, v87
	v_add_f32_e32 v5, 0xc2400000, v0
	v_max3_f32 v2, v2, v15, v103
	v_pk_mul_f32 v[6:7], v[188:189], v[160:161]
	v_and_b32_e32 v161, 0x7fffffff, v5
	v_mov_b32_e32 v188, v88
	v_max3_f32 v2, v2, v105, v107
	v_sub_f32_e32 v8, v6, v7
	v_pk_mul_f32 v[6:7], v[188:189], v[160:161]
	v_add_f32_e32 v5, 0xc2440000, v0
	v_max3_f32 v2, v2, v102, v104
	v_sub_f32_e32 v6, v6, v7
	v_and_b32_e32 v161, 0x7fffffff, v5
	v_mov_b32_e32 v188, v89
	v_add_f32_e32 v7, 0xc2480000, v0
	v_max3_f32 v2, v2, v106, v101
	v_pk_mul_f32 v[84:85], v[188:189], v[160:161]
	v_and_b32_e32 v161, 0x7fffffff, v7
	v_mov_b32_e32 v188, v90
	v_max3_f32 v2, v2, v100, v97
	v_sub_f32_e32 v5, v84, v85
	v_pk_mul_f32 v[84:85], v[188:189], v[160:161]
	v_and_b32_e32 v161, 0x7fffffff, v9
	v_mov_b32_e32 v188, v91
	v_add_f32_e32 v9, 0xc2600000, v0
	v_max3_f32 v2, v2, v98, v99
	v_sub_f32_e32 v7, v84, v85
	v_pk_mul_f32 v[84:85], v[188:189], v[160:161]
	v_and_b32_e32 v161, 0x7fffffff, v9
	v_mov_b32_e32 v188, v92
	v_max3_f32 v2, v2, v80, v81
	v_sub_f32_e32 v12, v84, v85
	v_pk_mul_f32 v[84:85], v[188:189], v[160:161]
	v_and_b32_e32 v161, 0x7fffffff, v11
	v_mov_b32_e32 v188, v93
	v_add_f32_e32 v11, 0xc2680000, v0
	v_max3_f32 v2, v2, v82, v8
	v_sub_f32_e32 v9, v84, v85
	v_pk_mul_f32 v[84:85], v[188:189], v[160:161]
	v_and_b32_e32 v161, 0x7fffffff, v11
	v_mov_b32_e32 v188, v94
	v_add_f32_e32 v0, 0xc26c0000, v0
	v_max3_f32 v2, v2, v6, v5
	v_sub_f32_e32 v14, v84, v85
	v_pk_mul_f32 v[84:85], v[188:189], v[160:161]
	v_and_b32_e32 v161, 0x7fffffff, v0
	v_mov_b32_e32 v188, v95
	v_max3_f32 v2, v2, v7, v12
	v_sub_f32_e32 v83, v84, v85
	v_pk_mul_f32 v[84:85], v[188:189], v[160:161]
	v_max3_f32 v2, v2, v9, v14
	v_sub_f32_e32 v11, v84, v85
	v_max3_f32 v0, v2, v83, v11
	ds_bpermute_b32 v2, v200, v0
	s_waitcnt lgkmcnt(0)
	v_max_f32_e32 v2, v0, v2
	v_sub_f32_e32 v0, v2, v204
	v_cmp_lt_f32_e32 vcc, 0x41000000, v0
	s_nop 1
	v_cndmask_b32_e32 v2, v204, v2, vcc
	v_sub_f32_e32 v0, v204, v2
	v_exp_f32_e32 v0, v0
	s_cbranch_vccz .LBB0_602
; DI void attn_item(const Params& p, int l, int item, char* lds) {
;     ...
;     if (__any(resc)) {
; #pragma unroll
;       for (int i = 0; i < 4; ++i)
; #pragma unroll
;         for (int e = 0; e < 16; ++e) O[i][e] *= alpha;
;     }
	v_pk_mul_f32 v[78:79], v[78:79], v[0:1] op_sel_hi:[1,0]
	v_pk_mul_f32 v[76:77], v[76:77], v[0:1] op_sel_hi:[1,0]
	v_pk_mul_f32 v[74:75], v[74:75], v[0:1] op_sel_hi:[1,0]
	v_pk_mul_f32 v[72:73], v[72:73], v[0:1] op_sel_hi:[1,0]
	v_pk_mul_f32 v[70:71], v[70:71], v[0:1] op_sel_hi:[1,0]
	v_pk_mul_f32 v[68:69], v[68:69], v[0:1] op_sel_hi:[1,0]
	v_pk_mul_f32 v[66:67], v[66:67], v[0:1] op_sel_hi:[1,0]
	v_pk_mul_f32 v[64:65], v[64:65], v[0:1] op_sel_hi:[1,0]
	v_pk_mul_f32 v[62:63], v[62:63], v[0:1] op_sel_hi:[1,0]
	v_pk_mul_f32 v[60:61], v[60:61], v[0:1] op_sel_hi:[1,0]
	v_pk_mul_f32 v[58:59], v[58:59], v[0:1] op_sel_hi:[1,0]
	v_pk_mul_f32 v[56:57], v[56:57], v[0:1] op_sel_hi:[1,0]
	v_pk_mul_f32 v[54:55], v[54:55], v[0:1] op_sel_hi:[1,0]
	v_pk_mul_f32 v[52:53], v[52:53], v[0:1] op_sel_hi:[1,0]
	v_pk_mul_f32 v[50:51], v[50:51], v[0:1] op_sel_hi:[1,0]
	v_pk_mul_f32 v[48:49], v[48:49], v[0:1] op_sel_hi:[1,0]
	v_pk_mul_f32 v[46:47], v[46:47], v[0:1] op_sel_hi:[1,0]
	v_pk_mul_f32 v[44:45], v[44:45], v[0:1] op_sel_hi:[1,0]
	v_pk_mul_f32 v[42:43], v[42:43], v[0:1] op_sel_hi:[1,0]
	v_pk_mul_f32 v[40:41], v[40:41], v[0:1] op_sel_hi:[1,0]
	v_pk_mul_f32 v[38:39], v[38:39], v[0:1] op_sel_hi:[1,0]
	v_pk_mul_f32 v[36:37], v[36:37], v[0:1] op_sel_hi:[1,0]
	v_pk_mul_f32 v[34:35], v[34:35], v[0:1] op_sel_hi:[1,0]
	v_pk_mul_f32 v[32:33], v[32:33], v[0:1] op_sel_hi:[1,0]
	v_pk_mul_f32 v[30:31], v[30:31], v[0:1] op_sel_hi:[1,0]
	v_pk_mul_f32 v[28:29], v[28:29], v[0:1] op_sel_hi:[1,0]
	v_pk_mul_f32 v[26:27], v[26:27], v[0:1] op_sel_hi:[1,0]
	v_pk_mul_f32 v[24:25], v[24:25], v[0:1] op_sel_hi:[1,0]
	v_pk_mul_f32 v[22:23], v[22:23], v[0:1] op_sel_hi:[1,0]
	v_pk_mul_f32 v[20:21], v[20:21], v[0:1] op_sel_hi:[1,0]
	v_pk_mul_f32 v[18:19], v[18:19], v[0:1] op_sel_hi:[1,0]
	v_pk_mul_f32 v[16:17], v[16:17], v[0:1] op_sel_hi:[1,0]
